# v82 plus MLP-norm loop with the next iteration's rows prefetched during the current iteration
# baseline (speedup 1.0000x reference)
.LBB0_1234:
	s_or_b64 exec, exec, s[0:1]
	s_mov_b32 s2, s18
	s_mov_b64 s[0:1], s[40:41]
	s_waitcnt lgkmcnt(0)
	v_mov_b32_e32 v0, v185
	s_barrier
	v_readlane_b32 s3, v252, 16
	v_mbcnt_lo_u32_b32 v0, -1, v0
	v_mbcnt_hi_u32_b32 v1, -1, v0
	v_add_u32_e32 v0, s3, v1
	v_ashrrev_i32_e32 v0, 6, v0
	v_readlane_b32 s3, v252, 50
	s_nop 1
	v_add_u32_e32 v32, s3, v0
	v_cmp_gt_i32_e32 vcc, s19, v32
	s_and_saveexec_b64 s[4:5], vcc
	s_cbranch_execz .LBB0_1241
	s_mul_i32 s6, s2, 0x66000
	s_mul_hi_i32 s3, s2, 0x66000
	s_add_u32 s6, s0, s6
	s_addc_u32 s7, s1, s3
	s_add_u32 s12, s0, 0x6200000
	s_addc_u32 s13, s1, 0
	s_lshl_b32 s2, s2, 10
	v_readlane_b32 s44, v252, 8
	s_ashr_i32 s3, s2, 31
	v_readlane_b32 s46, v252, 10
	v_readlane_b32 s47, v252, 11
	s_lshl_b64 s[2:3], s[2:3], 2
	s_mov_b64 s[10:11], s[46:47]
	v_lshlrev_b32_e32 v2, 2, v1
	s_add_u32 s2, s10, s2
	v_and_b32_e32 v34, 0xfc, v2
	s_addc_u32 s3, s11, s3
	v_lshlrev_b32_e32 v184, 2, v34
	v_lshl_add_u64 v[36:37], s[2:3], 0, v[184:185]
	v_readlane_b32 s2, v255, 8
	v_and_b32_e32 v1, 63, v1
	v_lshlrev_b32_e32 v38, 3, v1
	v_add_u32_e32 v40, s2, v0
	v_ashrrev_i32_e32 v41, 31, v40
	v_lshlrev_b64 v[0:1], 11, v[40:41]
	v_ashrrev_i32_e32 v33, 31, v32
	v_readlane_b32 s50, v252, 14
	v_or_b32_e32 v2, 0x100, v34
	v_or_b32_e32 v4, 0x200, v34
	v_or_b32_e32 v6, 0x300, v34
	v_lshl_add_u64 v[42:43], s[0:1], 0, v[0:1]
	v_lshlrev_b64 v[0:1], 11, v[32:33]
	s_mov_b32 s50, 0x41000000
	v_mov_b32_e32 v39, v185
	v_lshl_add_u64 v[44:45], s[0:1], 0, v[0:1]
	s_mov_b64 s[8:9], 0
	v_lshlrev_b32_e32 v46, 2, v2
	v_lshlrev_b32_e32 v48, 2, v4
	v_lshlrev_b32_e32 v50, 2, v6
	s_mov_b64 s[10:11], 0
	v_mov_b32_e32 v35, v32
	v_readlane_b32 s45, v252, 9
	v_readlane_b32 s48, v252, 12
	v_readlane_b32 s49, v252, 13
	v_readlane_b32 s51, v252, 15
	s_mov_b32 s0, 0x8000
	v_add_u32_e32 v152, 0xffff8000, v35
	v_lshl_add_u64 v[150:151], v[32:33], 0, s[10:11]
	v_cmp_gt_i32_e32 vcc, s0, v35
	v_mov_b32_e32 v153, s39
	v_mov_b32_e32 v154, s38
	v_cndmask_b32_e32 v150, v152, v150, vcc
	v_mov_b32_e32 v152, s13
	v_cndmask_b32_e32 v151, 0, v151, vcc
	v_cndmask_b32_e32 v153, v152, v153, vcc
	v_mov_b32_e32 v152, s12
	v_cndmask_b32_e32 v152, v152, v154, vcc
	v_lshlrev_b64 v[150:151], 12, v[150:151]
	v_lshl_add_u64 v[150:151], v[152:153], 0, v[150:151]
	v_lshlrev_b32_e32 v184, 2, v34
	v_lshl_add_u64 v[150:151], v[150:151], 0, v[184:185]
	global_load_dwordx4 v[218:221], v[150:151], off nt
	global_load_dwordx4 v[214:217], v[150:151], off offset:1024 nt
	global_load_dwordx4 v[210:213], v[150:151], off offset:2048 nt
	global_load_dwordx4 v[206:209], v[150:151], off offset:3072 nt
	v_add_u32_e32 v53, s62, v35
	v_cmp_gt_i32_e32 vcc, s19, v53
	s_nop 1
	v_cndmask_b32_e32 v223, v35, v53, vcc
	v_cndmask_b32_e32 v224, v32, v40, vcc
	v_cndmask_b32_e32 v225, v33, v41, vcc
	v_add_u32_e32 v158, 0xffff8000, v223
	v_lshl_add_u64 v[156:157], v[224:225], 0, s[10:11]
	v_cmp_gt_i32_e32 vcc, s0, v223
	v_mov_b32_e32 v159, s39
	v_mov_b32_e32 v160, s38
	v_cndmask_b32_e32 v156, v158, v156, vcc
	v_mov_b32_e32 v158, s13
	v_cndmask_b32_e32 v157, 0, v157, vcc
	v_cndmask_b32_e32 v159, v158, v159, vcc
	v_mov_b32_e32 v158, s12
	v_cndmask_b32_e32 v158, v158, v160, vcc
	v_lshlrev_b64 v[156:157], 12, v[156:157]
	v_lshl_add_u64 v[156:157], v[158:159], 0, v[156:157]
	v_lshl_add_u64 v[156:157], v[156:157], 0, v[184:185]
	global_load_dwordx4 v[202:205], v[156:157], off nt
	global_load_dwordx4 v[198:201], v[156:157], off offset:1024 nt
	global_load_dwordx4 v[194:197], v[156:157], off offset:2048 nt
	global_load_dwordx4 v[190:193], v[156:157], off offset:3072 nt
	v_mov_b32_e32 v222, 1
	s_branch .LBB0_1237

.LBB0_1237:
	v_lshlrev_b32_e32 v184, 2, v34
	v_add_u32_e32 v53, s62, v35
	v_cmp_gt_i32_e64 s[0:1], s19, v53
	v_min_i32_e32 v47, 0x8000, v35
	v_ashrrev_i32_e32 v47, 11, v47
	v_mul_hi_i32_i24_e32 v57, 0x6000, v47
	v_mul_i32_i24_e32 v56, 0x6000, v47
	v_lshl_add_u64 v[56:57], s[6:7], 0, v[56:57]
	s_mov_b64 s[2:3], 0x4000
	v_lshl_add_u64 v[54:55], v[56:57], 0, s[2:3]
	s_mov_b64 s[2:3], 0x3000
	v_lshl_add_u64 v[56:57], v[56:57], 0, s[2:3]
	v_lshl_add_u64 v[54:55], v[54:55], 0, v[184:185]
	v_lshl_add_u64 v[56:57], v[56:57], 0, v[184:185]
	global_load_dwordx4 v[70:73], v[36:37], off
	global_load_dwordx4 v[74:77], v[36:37], off offset:1024
	global_load_dwordx4 v[78:81], v[36:37], off offset:2048
	global_load_dwordx4 v[82:85], v[36:37], off offset:3072
	global_load_dwordx4 v[86:89], v[54:55], off
	global_load_dwordx4 v[90:93], v[54:55], off offset:1024
	global_load_dwordx4 v[94:97], v[54:55], off offset:2048
	global_load_dwordx4 v[98:101], v[54:55], off offset:3072
	global_load_dwordx4 v[102:105], v[56:57], off
	global_load_dwordx4 v[106:109], v[56:57], off offset:1024
	global_load_dwordx4 v[110:113], v[56:57], off offset:2048
	global_load_dwordx4 v[114:117], v[56:57], off offset:3072
	v_min_i32_e32 v47, 0x8000, v53
	v_ashrrev_i32_e32 v47, 11, v47
	v_mul_hi_i32_i24_e32 v61, 0x6000, v47
	v_mul_i32_i24_e32 v60, 0x6000, v47
	v_lshl_add_u64 v[60:61], s[6:7], 0, v[60:61]
	s_mov_b64 s[14:15], 0x4000
	v_lshl_add_u64 v[58:59], v[60:61], 0, s[14:15]
	s_mov_b64 s[14:15], 0x3000
	v_lshl_add_u64 v[60:61], v[60:61], 0, s[14:15]
	v_lshl_add_u64 v[58:59], v[58:59], 0, v[184:185]
	v_lshl_add_u64 v[60:61], v[60:61], 0, v[184:185]
	global_load_dwordx4 v[118:121], v[58:59], off
	global_load_dwordx4 v[122:125], v[58:59], off offset:1024
	global_load_dwordx4 v[126:129], v[58:59], off offset:2048
	global_load_dwordx4 v[130:133], v[58:59], off offset:3072
	global_load_dwordx4 v[134:137], v[60:61], off
	global_load_dwordx4 v[138:141], v[60:61], off offset:1024
	global_load_dwordx4 v[142:145], v[60:61], off offset:2048
	global_load_dwordx4 v[146:149], v[60:61], off offset:3072
	v_readfirstlane_b32 s14, v222
	v_mov_b32_e32 v222, 0
	s_nop 1
	s_cmp_eq_u32 s14, 1
	s_cbranch_scc1 .Lnp6_first
	s_waitcnt vmcnt(28)
	s_branch .Lnp6_have
.Lnp6_first:
	s_waitcnt vmcnt(20)
.Lnp6_have:
	v_mov_b64_e32 v[28:29], v[218:219]
	v_mov_b64_e32 v[30:31], v[220:221]
	v_mov_b64_e32 v[24:25], v[214:215]
	v_mov_b64_e32 v[26:27], v[216:217]
	v_mov_b64_e32 v[20:21], v[210:211]
	v_mov_b64_e32 v[22:23], v[212:213]
	v_mov_b64_e32 v[16:17], v[206:207]
	v_mov_b64_e32 v[18:19], v[208:209]
	v_mov_b64_e32 v[12:13], v[202:203]
	v_mov_b64_e32 v[14:15], v[204:205]
	v_mov_b64_e32 v[8:9], v[198:199]
	v_mov_b64_e32 v[10:11], v[200:201]
	v_mov_b64_e32 v[4:5], v[194:195]
	v_mov_b64_e32 v[6:7], v[196:197]
	v_mov_b64_e32 v[0:1], v[190:191]
	v_mov_b64_e32 v[2:3], v[192:193]
	v_readlane_b32 s2, v255, 11
	v_readlane_b32 s3, v255, 12
	s_nop 3
	s_add_u32 s14, s10, s2
	s_addc_u32 s15, s11, s3
	v_add_u32_e32 v226, s2, v35
	v_cmp_gt_i32_e32 vcc, s19, v226
	s_and_b64 vcc, exec, vcc
	s_cbranch_vccz .Lnp6_nopf
	s_mov_b32 s2, 0x8000
	v_add_u32_e32 v152, 0xffff8000, v226
	v_lshl_add_u64 v[150:151], v[32:33], 0, s[14:15]
	v_cmp_gt_i32_e32 vcc, s2, v226
	v_mov_b32_e32 v153, s39
	v_mov_b32_e32 v154, s38
	v_cndmask_b32_e32 v150, v152, v150, vcc
	v_mov_b32_e32 v152, s13
	v_cndmask_b32_e32 v151, 0, v151, vcc
	v_cndmask_b32_e32 v153, v152, v153, vcc
	v_mov_b32_e32 v152, s12
	v_cndmask_b32_e32 v152, v152, v154, vcc
	v_lshlrev_b64 v[150:151], 12, v[150:151]
	v_lshl_add_u64 v[150:151], v[152:153], 0, v[150:151]
	v_lshl_add_u64 v[150:151], v[150:151], 0, v[184:185]
	global_load_dwordx4 v[218:221], v[150:151], off nt
	global_load_dwordx4 v[214:217], v[150:151], off offset:1024 nt
	global_load_dwordx4 v[210:213], v[150:151], off offset:2048 nt
	global_load_dwordx4 v[206:209], v[150:151], off offset:3072 nt
	v_add_u32_e32 v227, s62, v226
	v_cmp_gt_i32_e32 vcc, s19, v227
	s_nop 1
	v_cndmask_b32_e32 v223, v226, v227, vcc
	v_cndmask_b32_e32 v224, v32, v40, vcc
	v_cndmask_b32_e32 v225, v33, v41, vcc
	v_add_u32_e32 v158, 0xffff8000, v223
	v_lshl_add_u64 v[156:157], v[224:225], 0, s[14:15]
	v_cmp_gt_i32_e32 vcc, s2, v223
	v_mov_b32_e32 v159, s39
	v_mov_b32_e32 v160, s38
	v_cndmask_b32_e32 v156, v158, v156, vcc
	v_mov_b32_e32 v158, s13
	v_cndmask_b32_e32 v157, 0, v157, vcc
	v_cndmask_b32_e32 v159, v158, v159, vcc
	v_mov_b32_e32 v158, s12
	v_cndmask_b32_e32 v158, v158, v160, vcc
	v_lshlrev_b64 v[156:157], 12, v[156:157]
	v_lshl_add_u64 v[156:157], v[158:159], 0, v[156:157]
	v_lshl_add_u64 v[156:157], v[156:157], 0, v[184:185]
	global_load_dwordx4 v[202:205], v[156:157], off nt
	global_load_dwordx4 v[198:201], v[156:157], off offset:1024 nt
	global_load_dwordx4 v[194:197], v[156:157], off offset:2048 nt
	global_load_dwordx4 v[190:193], v[156:157], off offset:3072 nt
	s_waitcnt vmcnt(8)
	s_branch .Lnp6_go

.Lnp6_go:
	v_lshl_add_u64 v[62:63], v[44:45], 0, v[38:39]
	v_add_co_u32_e32 v62, vcc, s17, v62
	s_nop 1
	v_addc_co_u32_e32 v63, vcc, 0, v63, vcc
	v_lshl_add_u64 v[64:65], v[42:43], 0, v[38:39]
	v_add_co_u32_e32 v64, vcc, s17, v64
	s_nop 1
	v_addc_co_u32_e32 v65, vcc, 0, v65, vcc
	v_mul_f32_e32 v47, v29, v29
	v_mul_f32_e32 v51, v31, v31
	v_fmac_f32_e32 v47, v28, v28
	v_fmac_f32_e32 v51, v30, v30
	v_add_f32_e32 v47, v47, v51
	v_mul_f32_e32 v49, v25, v25
	v_mul_f32_e32 v51, v27, v27
	v_fmac_f32_e32 v49, v24, v24
	v_fmac_f32_e32 v51, v26, v26
	v_add_f32_e32 v49, v49, v51
	v_add_f32_e32 v47, v47, v49
	v_mul_f32_e32 v49, v21, v21
	v_mul_f32_e32 v51, v23, v23
	v_fmac_f32_e32 v49, v20, v20
	v_fmac_f32_e32 v51, v22, v22
	v_add_f32_e32 v49, v49, v51
	v_add_f32_e32 v47, v47, v49
	v_mul_f32_e32 v49, v17, v17
	v_mul_f32_e32 v51, v19, v19
	v_fmac_f32_e32 v49, v16, v16
	v_fmac_f32_e32 v51, v18, v18
	v_add_f32_e32 v49, v49, v51
	v_add_f32_e32 v47, v47, v49
	ds_swizzle_b32 v49, v47 offset:swizzle(SWAP,1)
	s_waitcnt lgkmcnt(0)
	v_add_f32_e32 v47, v47, v49
	ds_swizzle_b32 v49, v47 offset:swizzle(SWAP,2)
	s_waitcnt lgkmcnt(0)
	v_add_f32_e32 v47, v47, v49
	ds_swizzle_b32 v49, v47 offset:swizzle(SWAP,4)
	s_waitcnt lgkmcnt(0)
	v_add_f32_e32 v47, v47, v49
	ds_swizzle_b32 v49, v47 offset:swizzle(SWAP,8)
	s_waitcnt lgkmcnt(0)
	v_add_f32_e32 v47, v47, v49
	ds_swizzle_b32 v49, v47 offset:swizzle(SWAP,16)
	s_waitcnt lgkmcnt(0)
	v_add_f32_e32 v47, v47, v49
	v_mov_b32_e32 v49, v47
	s_nop 1
	v_permlane32_swap_b32_e32 v47, v49
	v_add_f32_e32 v47, v47, v49
	v_fmamk_f32 v47, v47, 0x3a800000, v245
	s_mov_b32 s2, 0xf800000
	v_cmp_gt_f32_e32 vcc, s2, v47
	v_mul_f32_e32 v49, 0x4f800000, v47
	s_nop 0
	v_cndmask_b32_e32 v47, v47, v49, vcc
	v_sqrt_f32_e32 v49, v47
	s_nop 0
	v_add_u32_e32 v51, -1, v49
	v_fma_f32 v52, -v51, v49, v47
	v_cmp_ge_f32_e64 s[2:3], 0, v52
	v_add_u32_e32 v52, 1, v49
	s_nop 0
	v_cndmask_b32_e64 v51, v49, v51, s[2:3]
	v_fma_f32 v49, -v52, v49, v47
	v_cmp_lt_f32_e64 s[2:3], 0, v49
	s_nop 1
	v_cndmask_b32_e64 v49, v51, v52, s[2:3]
	v_mul_f32_e32 v51, 0x37800000, v49
	v_cndmask_b32_e32 v49, v49, v51, vcc
	v_cmp_class_f32_e32 vcc, v47, v250
	s_nop 1
	v_cndmask_b32_e32 v47, v49, v47, vcc
	v_div_scale_f32 v49, s[2:3], v47, v47, 1.0
	v_rcp_f32_e32 v51, v49
	s_nop 0
	v_fma_f32 v52, -v49, v51, 1.0
	v_fmac_f32_e32 v51, v52, v51
	v_div_scale_f32 v52, vcc, 1.0, v47, 1.0
	v_mul_f32_e32 v66, v52, v51
	v_fma_f32 v67, -v49, v66, v52
	v_fmac_f32_e32 v66, v67, v51
	v_fma_f32 v49, -v49, v66, v52
	v_div_fmas_f32 v49, v49, v51, v66
	v_div_fixup_f32 v52, v49, v47, 1.0
	v_pk_mul_f32 v[30:31], v[30:31], v[52:53] op_sel_hi:[1,0]
	v_pk_mul_f32 v[28:29], v[28:29], v[52:53] op_sel_hi:[1,0]
	v_pk_mul_f32 v[30:31], v[72:73], v[30:31]
	v_pk_mul_f32 v[28:29], v[70:71], v[28:29]
	v_pk_add_f32 v[86:87], v[86:87], 1.0 op_sel_hi:[1,0]
	v_pk_add_f32 v[88:89], v[88:89], 1.0 op_sel_hi:[1,0]
	v_pk_fma_f32 v[28:29], v[86:87], v[28:29], v[102:103]
	v_pk_fma_f32 v[30:31], v[88:89], v[30:31], v[104:105]
	v_cvt_pk_bf16_f32 v28, v28, v29
	v_cvt_pk_bf16_f32 v29, v30, v31
	global_store_dwordx2 v[62:63], v[28:29], off
	v_pk_mul_f32 v[26:27], v[26:27], v[52:53] op_sel_hi:[1,0]
	v_pk_mul_f32 v[24:25], v[24:25], v[52:53] op_sel_hi:[1,0]
	v_pk_mul_f32 v[26:27], v[76:77], v[26:27]
	v_pk_mul_f32 v[24:25], v[74:75], v[24:25]
	v_pk_add_f32 v[90:91], v[90:91], 1.0 op_sel_hi:[1,0]
	v_pk_add_f32 v[92:93], v[92:93], 1.0 op_sel_hi:[1,0]
	v_pk_fma_f32 v[24:25], v[90:91], v[24:25], v[106:107]
	v_pk_fma_f32 v[26:27], v[92:93], v[26:27], v[108:109]
	v_cvt_pk_bf16_f32 v24, v24, v25
	v_cvt_pk_bf16_f32 v25, v26, v27
	global_store_dwordx2 v[62:63], v[24:25], off offset:512
	v_pk_mul_f32 v[22:23], v[22:23], v[52:53] op_sel_hi:[1,0]
	v_pk_mul_f32 v[20:21], v[20:21], v[52:53] op_sel_hi:[1,0]
	v_pk_mul_f32 v[22:23], v[80:81], v[22:23]
	v_pk_mul_f32 v[20:21], v[78:79], v[20:21]
	v_pk_add_f32 v[94:95], v[94:95], 1.0 op_sel_hi:[1,0]
	v_pk_add_f32 v[96:97], v[96:97], 1.0 op_sel_hi:[1,0]
	v_pk_fma_f32 v[20:21], v[94:95], v[20:21], v[110:111]
	v_pk_fma_f32 v[22:23], v[96:97], v[22:23], v[112:113]
	v_cvt_pk_bf16_f32 v20, v20, v21
	v_cvt_pk_bf16_f32 v21, v22, v23
	global_store_dwordx2 v[62:63], v[20:21], off offset:1024
	v_pk_mul_f32 v[18:19], v[18:19], v[52:53] op_sel_hi:[1,0]
	v_pk_mul_f32 v[16:17], v[16:17], v[52:53] op_sel_hi:[1,0]
	v_pk_mul_f32 v[18:19], v[84:85], v[18:19]
	v_pk_mul_f32 v[16:17], v[82:83], v[16:17]
	v_pk_add_f32 v[98:99], v[98:99], 1.0 op_sel_hi:[1,0]
	v_pk_add_f32 v[100:101], v[100:101], 1.0 op_sel_hi:[1,0]
	v_pk_fma_f32 v[16:17], v[98:99], v[16:17], v[114:115]
	v_pk_fma_f32 v[18:19], v[100:101], v[18:19], v[116:117]
	v_cvt_pk_bf16_f32 v16, v16, v17
	v_cvt_pk_bf16_f32 v17, v18, v19
	global_store_dwordx2 v[62:63], v[16:17], off offset:1536
	s_and_saveexec_b64 s[2:3], s[0:1]
	s_cbranch_execz .LBB0_1236
	v_mul_f32_e32 v47, v13, v13
	v_mul_f32_e32 v51, v15, v15
	v_fmac_f32_e32 v47, v12, v12
	v_fmac_f32_e32 v51, v14, v14
	v_add_f32_e32 v47, v47, v51
	v_mul_f32_e32 v49, v9, v9
	v_mul_f32_e32 v51, v11, v11
	v_fmac_f32_e32 v49, v8, v8
	v_fmac_f32_e32 v51, v10, v10
	v_add_f32_e32 v49, v49, v51
	v_add_f32_e32 v47, v47, v49
	v_mul_f32_e32 v49, v5, v5
	v_mul_f32_e32 v51, v7, v7
	v_fmac_f32_e32 v49, v4, v4
	v_fmac_f32_e32 v51, v6, v6
	v_add_f32_e32 v49, v49, v51
	v_add_f32_e32 v47, v47, v49
	v_mul_f32_e32 v49, v1, v1
	v_mul_f32_e32 v51, v3, v3
	v_fmac_f32_e32 v49, v0, v0
	v_fmac_f32_e32 v51, v2, v2
	v_add_f32_e32 v49, v49, v51
	v_add_f32_e32 v47, v47, v49
	ds_swizzle_b32 v49, v47 offset:swizzle(SWAP,1)
	s_waitcnt lgkmcnt(0)
	v_add_f32_e32 v47, v47, v49
	ds_swizzle_b32 v49, v47 offset:swizzle(SWAP,2)
	s_waitcnt lgkmcnt(0)
	v_add_f32_e32 v47, v47, v49
	ds_swizzle_b32 v49, v47 offset:swizzle(SWAP,4)
	s_waitcnt lgkmcnt(0)
	v_add_f32_e32 v47, v47, v49
	ds_swizzle_b32 v49, v47 offset:swizzle(SWAP,8)
	s_waitcnt lgkmcnt(0)
	v_add_f32_e32 v47, v47, v49
	ds_swizzle_b32 v49, v47 offset:swizzle(SWAP,16)
	s_waitcnt lgkmcnt(0)
	v_add_f32_e32 v47, v47, v49
	v_mov_b32_e32 v49, v47
	s_nop 1
	v_permlane32_swap_b32_e32 v47, v49
	v_add_f32_e32 v47, v47, v49
	v_fmamk_f32 v47, v47, 0x3a800000, v245
	s_mov_b32 s0, 0xf800000
	v_cmp_gt_f32_e32 vcc, s0, v47
	v_mul_f32_e32 v49, 0x4f800000, v47
	s_nop 0
	v_cndmask_b32_e32 v47, v47, v49, vcc
	v_sqrt_f32_e32 v49, v47
	s_nop 0
	v_add_u32_e32 v51, -1, v49
	v_fma_f32 v52, -v51, v49, v47
	v_cmp_ge_f32_e64 s[0:1], 0, v52
	v_add_u32_e32 v52, 1, v49
	s_nop 0
	v_cndmask_b32_e64 v51, v49, v51, s[0:1]
	v_fma_f32 v49, -v52, v49, v47
	v_cmp_lt_f32_e64 s[0:1], 0, v49
	s_nop 1
	v_cndmask_b32_e64 v49, v51, v52, s[0:1]
	v_mul_f32_e32 v51, 0x37800000, v49
	v_cndmask_b32_e32 v49, v49, v51, vcc
	v_cmp_class_f32_e32 vcc, v47, v250
	s_nop 1
	v_cndmask_b32_e32 v47, v49, v47, vcc
	v_div_scale_f32 v49, s[0:1], v47, v47, 1.0
	v_rcp_f32_e32 v51, v49
	s_nop 0
	v_fma_f32 v52, -v49, v51, 1.0
	v_fmac_f32_e32 v51, v52, v51
	v_div_scale_f32 v52, vcc, 1.0, v47, 1.0
	v_mul_f32_e32 v66, v52, v51
	v_fma_f32 v67, -v49, v66, v52
	v_fmac_f32_e32 v66, v67, v51
	v_fma_f32 v49, -v49, v66, v52
	v_div_fmas_f32 v49, v49, v51, v66
	v_div_fixup_f32 v52, v49, v47, 1.0
	v_pk_mul_f32 v[14:15], v[14:15], v[52:53] op_sel_hi:[1,0]
	v_pk_mul_f32 v[12:13], v[12:13], v[52:53] op_sel_hi:[1,0]
	v_pk_mul_f32 v[14:15], v[72:73], v[14:15]
	v_pk_mul_f32 v[12:13], v[70:71], v[12:13]
	v_pk_add_f32 v[118:119], v[118:119], 1.0 op_sel_hi:[1,0]
	v_pk_add_f32 v[120:121], v[120:121], 1.0 op_sel_hi:[1,0]
	v_pk_fma_f32 v[12:13], v[118:119], v[12:13], v[134:135]
	v_pk_fma_f32 v[14:15], v[120:121], v[14:15], v[136:137]
	v_cvt_pk_bf16_f32 v12, v12, v13
	v_cvt_pk_bf16_f32 v13, v14, v15
	global_store_dwordx2 v[64:65], v[12:13], off
	v_pk_mul_f32 v[10:11], v[10:11], v[52:53] op_sel_hi:[1,0]
	v_pk_mul_f32 v[8:9], v[8:9], v[52:53] op_sel_hi:[1,0]
	v_pk_mul_f32 v[10:11], v[76:77], v[10:11]
	v_pk_mul_f32 v[8:9], v[74:75], v[8:9]
	v_pk_add_f32 v[122:123], v[122:123], 1.0 op_sel_hi:[1,0]
	v_pk_add_f32 v[124:125], v[124:125], 1.0 op_sel_hi:[1,0]
	v_pk_fma_f32 v[8:9], v[122:123], v[8:9], v[138:139]
	v_pk_fma_f32 v[10:11], v[124:125], v[10:11], v[140:141]
	v_cvt_pk_bf16_f32 v8, v8, v9
	v_cvt_pk_bf16_f32 v9, v10, v11
	global_store_dwordx2 v[64:65], v[8:9], off offset:512
	v_pk_mul_f32 v[6:7], v[6:7], v[52:53] op_sel_hi:[1,0]
	v_pk_mul_f32 v[4:5], v[4:5], v[52:53] op_sel_hi:[1,0]
	v_pk_mul_f32 v[6:7], v[80:81], v[6:7]
	v_pk_mul_f32 v[4:5], v[78:79], v[4:5]
	v_pk_add_f32 v[126:127], v[126:127], 1.0 op_sel_hi:[1,0]
	v_pk_add_f32 v[128:129], v[128:129], 1.0 op_sel_hi:[1,0]
	v_pk_fma_f32 v[4:5], v[126:127], v[4:5], v[142:143]
	v_pk_fma_f32 v[6:7], v[128:129], v[6:7], v[144:145]
	v_cvt_pk_bf16_f32 v4, v4, v5
	v_cvt_pk_bf16_f32 v5, v6, v7
	global_store_dwordx2 v[64:65], v[4:5], off offset:1024
	v_pk_mul_f32 v[2:3], v[2:3], v[52:53] op_sel_hi:[1,0]
	v_pk_mul_f32 v[0:1], v[0:1], v[52:53] op_sel_hi:[1,0]
	v_pk_mul_f32 v[2:3], v[84:85], v[2:3]
	v_pk_mul_f32 v[0:1], v[82:83], v[0:1]
	v_pk_add_f32 v[130:131], v[130:131], 1.0 op_sel_hi:[1,0]
	v_pk_add_f32 v[132:133], v[132:133], 1.0 op_sel_hi:[1,0]
	v_pk_fma_f32 v[0:1], v[130:131], v[0:1], v[146:147]
	v_pk_fma_f32 v[2:3], v[132:133], v[2:3], v[148:149]
	v_cvt_pk_bf16_f32 v0, v0, v1
	v_cvt_pk_bf16_f32 v1, v2, v3
	global_store_dwordx2 v[64:65], v[0:1], off offset:1536
	s_branch .LBB0_1236
